# v13 + FFN-down K loops: touch the residual tile's HI/LO cache lines (4 one-dword-per-line loads per wave) during iterations 17-20 of 22 so the EpiResid epilogue reads hit cache
# baseline (speedup 1.0000x reference)
; __device__ __forceinline__ int fresh_tid(int wave_s) { return wave_s * 64 + lane_id(); }
; #define PG8_STAGE(bufoff, gbase, voff) do { _Pragma("unroll") for (int _i = 0; _i < 2; ++_i) \
;         __builtin_amdgcn_global_load_lds((const unsigned*)((const char*)(gbase) + (voff)[_i]), (LAS unsigned*)(lds + (bufoff) + ldsw + _i * 8192), 16, 0, 0); } while (0)
; #define PG8_WAIT_V(n) asm volatile("s_waitcnt vmcnt(" #n ")" ::: "memory")
; template <class Epi>
; __device__ __forceinline__ void gemm_phase(LAS unsigned char* lds, int wave_s, const Gemm g, const StaticOrder S, const Epi E) {
;     const int tid = fresh_tid(wave_s);
;     const int wid = __builtin_amdgcn_readfirstlane(tid >> 6), lane = tid & 63, wr = wid >> 2, wc = wid & 3, fr = lane & 15, fq = lane >> 4;
;     const int K = g.K, nt = K / BK, lda = g.lda;
;     unsigned voffA[2], voffB[2];
; #pragma unroll
;     for (int i = 0; i < 2; ++i) { int R, C; stage_rc(tid * 16 + i * 8192, R, C); const int Rb = Epi::PERM ? ((R & ~31) + perm32(R & 31)) : R;
;         voffA[i] = (unsigned)(R * lda + C) * 2u; voffB[i] = (unsigned)(Rb * K + C) * 2u; }
;     const size_t kstep = (size_t)(BK * 2);
;     const size_t hstepA = (size_t)HALF * lda * 2, hstepB = (size_t)HALF * K * 2;
;     const size_t tstepA = 2 * hstepA, tstepB = 2 * hstepB;
;     const unsigned ldsw = (unsigned)wid * 1024u;
;     const int aoff = lds_byte(wr * 64 + fr, fq * 8), boff = lds_byte(wc * 32 + fr, fq * 8);
;     ...
;     Unit cur, nxt; int ui = 0;
;     if (!S.next(0, cur)) return;
;     f32x4 acc[2][2][4][2];
; #pragma unroll
;     for (int a = 0; a < 2; ++a)
; #pragma unroll
;         for (int b = 0; b < 2; ++b)
; #pragma unroll
;             for (int m = 0; m < 4; ++m)
; #pragma unroll
;                 for (int n = 0; n < 2; ++n) acc[a][b][m][n] = (f32x4){0.f, 0.f, 0.f, 0.f};
;     bf16x8 At[4][2], B0[2][2], B1[2][2];
;     const char* cA = (const char*)g.A + (size_t)cur.pm * tstepA; const char* cB = (const char*)g.Bt + (size_t)cur.pn * tstepB;
;     PG8_STAGE(PG8_SB(0, 0), cB, voffB); PG8_STAGE(PG8_SB(0, 1), cB + hstepB, voffB); PG8_STAGE(PG8_SA(0, 0), cA, voffA); PG8_STAGE(PG8_SA(0, 1), cA + hstepA, voffA);
;     if (wr == 1) PG8_BAR;
;     PG8_WAIT_V(2); PG8_BAR;
;     PG8_STAGE(PG8_SB(1, 0), cB + kstep, voffB); PG8_STAGE(PG8_SA(1, 0), cA + kstep, voffA); PG8_STAGE(PG8_SB(1, 1), cB + hstepB + kstep, voffB);
;     PG8_WAIT_V(6); PG8_BAR;
.LBB0_224:
	s_or_b64 exec, exec, s[0:1]
	v_readlane_b32 s0, v252, 19
	v_readlane_b32 s1, v252, 20
	s_waitcnt lgkmcnt(0)
	s_barrier
	v_add_u32_e32 v243, s92, v241
	v_lshrrev_b32_e32 v242, 2, v243
	v_and_b32_e32 v243, 3, v243
	v_lshlrev_b32_e32 v243, 7, v243
	v_lshl_add_u32 v243, v242, 11, v243
	v_cndmask_b32_e64 v2, 0, 1, s[0:1]
	v_cmp_ne_u32_e64 s[6:7], 1, v2
	v_mbcnt_lo_u32_b32 v10, -1, 0
	v_mbcnt_hi_u32_b32 v10, -1, v10
	s_andn2_b64 vcc, exec, s[0:1]
	v_add_u32_e32 v0, s92, v10
	v_writelane_b32 v254, s6, 28
	v_readfirstlane_b32 s0, v0
	s_nop 0
	v_writelane_b32 v254, s7, 29
	s_cbranch_vccnz .LBB0_264
	v_lshlrev_b32_e32 v6, 4, v0
	v_add_u32_e32 v3, 0x2000, v6
	v_ashrrev_i32_e32 v2, 31, v3
	v_lshrrev_b32_e32 v2, 22, v2
	v_add_u32_e32 v2, v3, v2
	v_ashrrev_i32_e32 v2, 10, v2
	v_mul_i32_i24_e32 v4, 0x400, v2
	v_sub_u32_e32 v3, v3, v4
	v_lshrrev_b32_e32 v4, 4, v3
	v_bitop3_b32 v5, v4, v3, 32 bitop3:0x6c
	v_ashrrev_i32_e32 v3, 31, v5
	v_lshrrev_b32_e32 v3, 26, v3
	v_add_u32_e32 v7, v5, v3
	v_lshlrev_b32_e32 v4, 3, v2
	v_ashrrev_i32_e32 v3, 6, v7
	v_and_b32_e32 v4, -16, v4
	v_add_u32_e32 v8, v3, v4
	v_and_b32_e32 v4, 3, v3
	s_mov_b32 s6, 0xffffe0
	v_lshrrev_b32_e32 v9, 2, v8
	v_lshlrev_b32_e32 v11, 1, v8
	v_and_or_b32 v4, v8, s6, v4
	v_and_b32_e32 v9, 4, v9
	v_and_b32_e32 v11, 24, v11
	v_and_b32_e32 v7, 0xc0, v7
	v_or3_b32 v4, v4, v9, v11
	v_sub_u32_e32 v5, v5, v7
	v_mov_b32_e32 v14, 1
	v_mul_u32_u24_e32 v9, 0xb00, v4
	v_lshlrev_b32_e32 v4, 5, v2
	v_ashrrev_i16_sdwa v5, v14, sext(v5) dst_sel:DWORD dst_unused:UNUSED_PAD src0_sel:DWORD src1_sel:BYTE_0
	v_and_b32_e32 v4, 32, v4
	v_bfe_i32 v5, v5, 0, 16
	s_movk_i32 s4, 0xb00
	v_add_u32_e32 v7, v4, v5
	v_mul_lo_u32 v8, v8, s4
	v_add_lshl_u32 v130, v9, v7, 1
	v_add_lshl_u32 v132, v7, v8, 1
	v_bfe_i32 v7, v0, 27, 1
	v_lshrrev_b32_e32 v7, 22, v7
	v_add_u32_e32 v7, v6, v7
	v_and_b32_e32 v7, 0xfffffc00, v7
	v_sub_u32_e32 v6, v6, v7
	v_lshrrev_b32_e32 v7, 4, v6
	v_bitop3_b32 v9, v7, v6, 32 bitop3:0x6c
	v_ashrrev_i32_e32 v7, 31, v0
	v_lshrrev_b32_e32 v7, 26, v7
	v_ashrrev_i32_e32 v6, 31, v9
	v_add_u32_e32 v0, v0, v7
	v_lshrrev_b32_e32 v6, 26, v6
	v_ashrrev_i32_e32 v7, 6, v0
	v_add_u32_e32 v11, v9, v6
	v_lshlrev_b32_e32 v0, 3, v7
	v_ashrrev_i32_e32 v6, 6, v11
	v_and_b32_e32 v0, -16, v0
	v_add_u32_e32 v12, v6, v0
	v_and_b32_e32 v0, 3, v6
	v_lshrrev_b32_e32 v8, 2, v12
	v_lshlrev_b32_e32 v13, 1, v12
	v_and_b32_e32 v11, 0xc0, v11
	v_and_or_b32 v0, v12, s6, v0
	v_and_b32_e32 v8, 4, v8
	v_and_b32_e32 v13, 24, v13
	v_sub_u32_e32 v9, v9, v11
	s_ashr_i32 s1, s0, 6
	v_or3_b32 v0, v0, v8, v13
	v_lshlrev_b32_e32 v8, 5, v7
	v_ashrrev_i16_sdwa v9, v14, sext(v9) dst_sel:DWORD dst_unused:UNUSED_PAD src0_sel:DWORD src1_sel:BYTE_0
	s_lshl_b32 s20, s1, 10
	v_and_b32_e32 v8, 32, v8
	v_bfe_i32 v9, v9, 0, 16
	v_mul_u32_u24_e32 v0, 0xb00, v0
	v_add_u32_e32 v11, v8, v9
	s_add_i32 s21, s20, 0
	v_readlane_b32 s6, v255, 27
	v_add_lshl_u32 v0, v0, v11, 1
	s_add_i32 m0, s21, 0x10000
	v_readlane_b32 s7, v255, 28
	v_mul_lo_u32 v12, v12, s4
	v_add_lshl_u32 v134, v11, v12, 1
	s_add_i32 s22, s21, 0x2000
	s_add_i32 s23, s21, 0x4000
	s_add_i32 s24, s21, 0x6000
	global_load_lds_dwordx4 v0, s[6:7]
	s_add_i32 m0, s21, 0x12000
	s_ashr_i32 s4, s0, 8
	global_load_lds_dwordx4 v130, s[6:7]
	v_readlane_b32 s6, v255, 21
	s_add_i32 m0, s21, 0x14000
	v_readlane_b32 s7, v255, 22
	s_nop 4
	global_load_lds_dwordx4 v0, s[6:7]
	s_add_i32 m0, s21, 0x16000
	s_cmp_eq_u32 s4, 1
	global_load_lds_dwordx4 v130, s[6:7]
	v_readlane_b32 s6, v255, 23
	s_mov_b32 m0, s21
	v_readlane_b32 s7, v255, 24
	s_cselect_b64 s[42:43], -1, 0
	s_cmp_lg_u32 s4, 1
	s_nop 2
	global_load_lds_dwordx4 v134, s[6:7]
	s_mov_b32 m0, s22
	s_nop 0
	global_load_lds_dwordx4 v132, s[6:7]
	v_readlane_b32 s6, v255, 25
	s_mov_b32 m0, s23
	v_readlane_b32 s7, v255, 26
	s_nop 4
	global_load_lds_dwordx4 v134, s[6:7]
	s_mov_b32 m0, s24
	s_nop 0
	global_load_lds_dwordx4 v132, s[6:7]
	s_cbranch_scc1 .LBB0_227
	s_barrier

; #define PG8_STAGE(bufoff, gbase, voff) do { _Pragma("unroll") for (int _i = 0; _i < 2; ++_i) \
;         __builtin_amdgcn_global_load_lds((const unsigned*)((const char*)(gbase) + (voff)[_i]), (LAS unsigned*)(lds + (bufoff) + ldsw + _i * 8192), 16, 0, 0); } while (0)
; #define PG8_LDA(dst, b, h) do { _Pragma("unroll") for (int m = 0; m < 4; ++m) _Pragma("unroll") for (int k = 0; k < 2; ++k) dst[m][k] = *(const LAS bf16x8*)(lds + PG8_SA(b, h) + aoff + m * 2048 + k * 1024); } while (0)
; #define PG8_LDB(dst, b, h) do { _Pragma("unroll") for (int n = 0; n < 2; ++n) _Pragma("unroll") for (int k = 0; k < 2; ++k) dst[n][k] = *(const LAS bf16x8*)(lds + PG8_SB(b, h) + boff + n * 2048 + k * 1024); } while (0)
; #define PG8_SCHED __builtin_amdgcn_sched_barrier(0)
; template <class Epi>
; __device__ __forceinline__ void gemm_phase(LAS unsigned char* lds, int wave_s, const Gemm g, const StaticOrder S, const Epi E) {
;     ...
;         for (int t = 0; t < nt; t += 2) {
;             const bool last = (t == nt - 2);
;             const char* a1 = cA + (size_t)(t + 1) * kstep;
;             const char* a2 = last ? nA : cA + (size_t)(t + 2) * kstep; const char* b2 = last ? nB : cB + (size_t)(t + 2) * kstep;
;             const char* a3 = a2 + kstep; const char* b3 = b2 + kstep;
;             PG8_LDB(B0, 0, 0); PG8_LDB(B1, 0, 1); PG8_SCHED; PG8_LDA(At, 0, 0); PG8_STAGE(PG8_SA(1, 1), a1 + hstepA, voffA);
;     __device__ __forceinline__ void operator()(const f32x4 (&acc)[2][2][4][2], const Unit& u, int wr, int wc, int fr, int fq) const {
;     ...
;                     const size_t off = (size_t)row * DM + col0 + bj * HALF;
;                     const u32x4 hh = *(const u32x4*)(HI + off), ll = *(const u32x4*)(LO + off);
.LBB0_241:
	s_sub_i32 s14, s34, 32
	s_cmp_gt_u32 s14, 6
	s_cbranch_scc1 .Lpf_f1d_skip
	s_cmp_lt_u32 s14, 4
	s_cbranch_scc0 .Lpf_f1d_lo
	s_mov_b64 s[100:101], s[38:39]
	s_branch .Lpf_f1d_go
.Lpf_f1d_lo:
	v_readlane_b32 s100, v250, 49
	v_readlane_b32 s101, v250, 50
.Lpf_f1d_go:
	s_lshl_b32 s15, s31, 19
	s_and_b32 s14, s14, 2
	s_lshl_b32 s14, s14, 17
	s_add_u32 s15, s15, s14
	s_lshl_b32 s14, s4, 9
	s_add_u32 s15, s15, s14
	s_add_u32 s100, s100, s15
	s_addc_u32 s101, s101, 0
	s_nop 0
	global_load_dword v242, v243, s[100:101]

; __device__ __forceinline__ int fresh_tid(int wave_s) { return wave_s * 64 + lane_id(); }
; #define PG8_STAGE(bufoff, gbase, voff) do { _Pragma("unroll") for (int _i = 0; _i < 2; ++_i) \
;         __builtin_amdgcn_global_load_lds((const unsigned*)((const char*)(gbase) + (voff)[_i]), (LAS unsigned*)(lds + (bufoff) + ldsw + _i * 8192), 16, 0, 0); } while (0)
; #define PG8_WAIT_V(n) asm volatile("s_waitcnt vmcnt(" #n ")" ::: "memory")
; template <class Epi>
; __device__ __forceinline__ void gemm_phase(LAS unsigned char* lds, int wave_s, const Gemm g, const StaticOrder S, const Epi E) {
;     const int tid = fresh_tid(wave_s);
;     const int wid = __builtin_amdgcn_readfirstlane(tid >> 6), lane = tid & 63, wr = wid >> 2, wc = wid & 3, fr = lane & 15, fq = lane >> 4;
;     const int K = g.K, nt = K / BK, lda = g.lda;
;     unsigned voffA[2], voffB[2];
; #pragma unroll
;     for (int i = 0; i < 2; ++i) { int R, C; stage_rc(tid * 16 + i * 8192, R, C); const int Rb = Epi::PERM ? ((R & ~31) + perm32(R & 31)) : R;
;         voffA[i] = (unsigned)(R * lda + C) * 2u; voffB[i] = (unsigned)(Rb * K + C) * 2u; }
;     const size_t kstep = (size_t)(BK * 2);
;     const size_t hstepA = (size_t)HALF * lda * 2, hstepB = (size_t)HALF * K * 2;
;     const size_t tstepA = 2 * hstepA, tstepB = 2 * hstepB;
;     const unsigned ldsw = (unsigned)wid * 1024u;
;     const int aoff = lds_byte(wr * 64 + fr, fq * 8), boff = lds_byte(wc * 32 + fr, fq * 8);
;     ...
;     Unit cur, nxt; int ui = 0;
;     if (!S.next(0, cur)) return;
;     f32x4 acc[2][2][4][2];
; #pragma unroll
;     for (int a = 0; a < 2; ++a)
; #pragma unroll
;         for (int b = 0; b < 2; ++b)
; #pragma unroll
;             for (int m = 0; m < 4; ++m)
; #pragma unroll
;                 for (int n = 0; n < 2; ++n) acc[a][b][m][n] = (f32x4){0.f, 0.f, 0.f, 0.f};
;     bf16x8 At[4][2], B0[2][2], B1[2][2];
;     const char* cA = (const char*)g.A + (size_t)cur.pm * tstepA; const char* cB = (const char*)g.Bt + (size_t)cur.pn * tstepB;
;     PG8_STAGE(PG8_SB(0, 0), cB, voffB); PG8_STAGE(PG8_SB(0, 1), cB + hstepB, voffB); PG8_STAGE(PG8_SA(0, 0), cA, voffA); PG8_STAGE(PG8_SA(0, 1), cA + hstepA, voffA);
;     if (wr == 1) PG8_BAR;
;     PG8_WAIT_V(2); PG8_BAR;
;     PG8_STAGE(PG8_SB(1, 0), cB + kstep, voffB); PG8_STAGE(PG8_SA(1, 0), cA + kstep, voffA); PG8_STAGE(PG8_SB(1, 1), cB + hstepB + kstep, voffB);
;     PG8_WAIT_V(6); PG8_BAR;
.LBB0_1230:
	s_or_b64 exec, exec, s[0:1]
	v_readlane_b32 s0, v254, 28
	s_waitcnt lgkmcnt(0)
	s_barrier
	v_add_u32_e32 v243, s92, v241
	v_lshrrev_b32_e32 v242, 2, v243
	v_and_b32_e32 v243, 3, v243
	v_lshlrev_b32_e32 v243, 7, v243
	v_lshl_add_u32 v243, v242, 11, v243
	v_mbcnt_lo_u32_b32 v10, -1, 0
	v_mbcnt_hi_u32_b32 v10, -1, v10
	v_readlane_b32 s1, v254, 29
	v_add_u32_e32 v0, s92, v10
	s_and_b64 vcc, exec, s[0:1]
	v_readfirstlane_b32 s0, v0
	s_cbranch_vccnz .LBB0_1270
	v_lshlrev_b32_e32 v6, 4, v0
	v_add_u32_e32 v3, 0x2000, v6
	v_ashrrev_i32_e32 v2, 31, v3
	v_lshrrev_b32_e32 v2, 22, v2
	v_add_u32_e32 v2, v3, v2
	v_ashrrev_i32_e32 v2, 10, v2
	v_mul_i32_i24_e32 v4, 0x400, v2
	v_sub_u32_e32 v3, v3, v4
	v_lshrrev_b32_e32 v4, 4, v3
	v_bitop3_b32 v5, v4, v3, 32 bitop3:0x6c
	v_ashrrev_i32_e32 v3, 31, v5
	v_lshrrev_b32_e32 v3, 26, v3
	v_add_u32_e32 v7, v5, v3
	v_lshlrev_b32_e32 v4, 3, v2
	v_ashrrev_i32_e32 v3, 6, v7
	v_and_b32_e32 v4, -16, v4
	v_add_u32_e32 v8, v3, v4
	v_and_b32_e32 v4, 3, v3
	s_mov_b32 s6, 0xffffe0
	v_lshrrev_b32_e32 v9, 2, v8
	v_lshlrev_b32_e32 v11, 1, v8
	v_and_or_b32 v4, v8, s6, v4
	v_and_b32_e32 v9, 4, v9
	v_and_b32_e32 v11, 24, v11
	v_and_b32_e32 v7, 0xc0, v7
	v_or3_b32 v4, v4, v9, v11
	v_sub_u32_e32 v5, v5, v7
	v_mov_b32_e32 v14, 1
	v_mul_u32_u24_e32 v9, 0xb00, v4
	v_lshlrev_b32_e32 v4, 5, v2
	v_ashrrev_i16_sdwa v5, v14, sext(v5) dst_sel:DWORD dst_unused:UNUSED_PAD src0_sel:DWORD src1_sel:BYTE_0
	v_and_b32_e32 v4, 32, v4
	v_bfe_i32 v5, v5, 0, 16
	s_movk_i32 s4, 0xb00
	v_add_u32_e32 v7, v4, v5
	v_mul_lo_u32 v8, v8, s4
	v_add_lshl_u32 v130, v9, v7, 1
	v_add_lshl_u32 v132, v7, v8, 1
	v_bfe_i32 v7, v0, 27, 1
	v_lshrrev_b32_e32 v7, 22, v7
	v_add_u32_e32 v7, v6, v7
	v_and_b32_e32 v7, 0xfffffc00, v7
	v_sub_u32_e32 v6, v6, v7
	v_lshrrev_b32_e32 v7, 4, v6
	v_bitop3_b32 v9, v7, v6, 32 bitop3:0x6c
	v_ashrrev_i32_e32 v7, 31, v0
	v_lshrrev_b32_e32 v7, 26, v7
	v_ashrrev_i32_e32 v6, 31, v9
	v_add_u32_e32 v0, v0, v7
	v_lshrrev_b32_e32 v6, 26, v6
	v_ashrrev_i32_e32 v7, 6, v0
	v_add_u32_e32 v11, v9, v6
	v_lshlrev_b32_e32 v0, 3, v7
	v_ashrrev_i32_e32 v6, 6, v11
	v_and_b32_e32 v0, -16, v0
	v_add_u32_e32 v12, v6, v0
	v_and_b32_e32 v0, 3, v6
	v_lshrrev_b32_e32 v8, 2, v12
	v_lshlrev_b32_e32 v13, 1, v12
	v_and_b32_e32 v11, 0xc0, v11
	v_and_or_b32 v0, v12, s6, v0
	v_and_b32_e32 v8, 4, v8
	v_and_b32_e32 v13, 24, v13
	v_sub_u32_e32 v9, v9, v11
	s_ashr_i32 s1, s0, 6
	v_or3_b32 v0, v0, v8, v13
	v_lshlrev_b32_e32 v8, 5, v7
	v_ashrrev_i16_sdwa v9, v14, sext(v9) dst_sel:DWORD dst_unused:UNUSED_PAD src0_sel:DWORD src1_sel:BYTE_0
	s_lshl_b32 s20, s1, 10
	v_and_b32_e32 v8, 32, v8
	v_bfe_i32 v9, v9, 0, 16
	v_mul_u32_u24_e32 v0, 0xb00, v0
	v_add_u32_e32 v11, v8, v9
	s_add_i32 s21, s20, 0
	v_readlane_b32 s6, v253, 25
	v_add_lshl_u32 v0, v0, v11, 1
	s_add_i32 m0, s21, 0x10000
	v_readlane_b32 s7, v253, 26
	v_mul_lo_u32 v12, v12, s4
	v_add_lshl_u32 v134, v11, v12, 1
	s_add_i32 s22, s21, 0x2000
	s_add_i32 s23, s21, 0x4000
	s_add_i32 s24, s21, 0x6000
	global_load_lds_dwordx4 v0, s[6:7]
	s_add_i32 m0, s21, 0x12000
	s_ashr_i32 s4, s0, 8
	global_load_lds_dwordx4 v130, s[6:7]
	v_readlane_b32 s6, v253, 23
	s_add_i32 m0, s21, 0x14000
	v_readlane_b32 s7, v253, 24
	s_nop 4
	global_load_lds_dwordx4 v0, s[6:7]
	s_add_i32 m0, s21, 0x16000
	s_cmp_eq_u32 s4, 1
	global_load_lds_dwordx4 v130, s[6:7]
	v_readlane_b32 s6, v255, 23
	s_mov_b32 m0, s21
	v_readlane_b32 s7, v255, 24
	s_cselect_b64 s[38:39], -1, 0
	s_cmp_lg_u32 s4, 1
	s_nop 2
	global_load_lds_dwordx4 v134, s[6:7]
	s_mov_b32 m0, s22
	s_nop 0
	global_load_lds_dwordx4 v132, s[6:7]
	v_readlane_b32 s6, v255, 25
	s_mov_b32 m0, s23
	v_readlane_b32 s7, v255, 26
	s_nop 4
	global_load_lds_dwordx4 v134, s[6:7]
	s_mov_b32 m0, s24
	s_nop 0
	global_load_lds_dwordx4 v132, s[6:7]
	s_cbranch_scc1 .LBB0_1233
	s_barrier

; #define PG8_STAGE(bufoff, gbase, voff) do { _Pragma("unroll") for (int _i = 0; _i < 2; ++_i) \
;         __builtin_amdgcn_global_load_lds((const unsigned*)((const char*)(gbase) + (voff)[_i]), (LAS unsigned*)(lds + (bufoff) + ldsw + _i * 8192), 16, 0, 0); } while (0)
; #define PG8_LDA(dst, b, h) do { _Pragma("unroll") for (int m = 0; m < 4; ++m) _Pragma("unroll") for (int k = 0; k < 2; ++k) dst[m][k] = *(const LAS bf16x8*)(lds + PG8_SA(b, h) + aoff + m * 2048 + k * 1024); } while (0)
; #define PG8_LDB(dst, b, h) do { _Pragma("unroll") for (int n = 0; n < 2; ++n) _Pragma("unroll") for (int k = 0; k < 2; ++k) dst[n][k] = *(const LAS bf16x8*)(lds + PG8_SB(b, h) + boff + n * 2048 + k * 1024); } while (0)
; #define PG8_SCHED __builtin_amdgcn_sched_barrier(0)
; template <class Epi>
; __device__ __forceinline__ void gemm_phase(LAS unsigned char* lds, int wave_s, const Gemm g, const StaticOrder S, const Epi E) {
;     ...
;         for (int t = 0; t < nt; t += 2) {
;             const bool last = (t == nt - 2);
;             const char* a1 = cA + (size_t)(t + 1) * kstep;
;             const char* a2 = last ? nA : cA + (size_t)(t + 2) * kstep; const char* b2 = last ? nB : cB + (size_t)(t + 2) * kstep;
;             const char* a3 = a2 + kstep; const char* b3 = b2 + kstep;
;             PG8_LDB(B0, 0, 0); PG8_LDB(B1, 0, 1); PG8_SCHED; PG8_LDA(At, 0, 0); PG8_STAGE(PG8_SA(1, 1), a1 + hstepA, voffA);
.LBB0_1247:
	s_sub_i32 s14, s34, 32
	s_cmp_gt_u32 s14, 6
	s_cbranch_scc1 .Lpf_f2d_skip
	s_cmp_lt_u32 s14, 4
	s_cbranch_scc0 .Lpf_f2d_lo
	v_readlane_b32 s100, v253, 35
	v_readlane_b32 s101, v253, 36
	s_branch .Lpf_f2d_go
